# NA window/ctx tiles after the first active tile use lean path: bias+mask folded into MFMA C init, reference max from first tile, ones-MFMA row sums, lazy pow2 rescale guard
# speedup vs baseline: 1.0212x; 1.0002x over previous
.Lna_exit:
	s_nop 7
	s_nop 7
	v_fmac_f32_e32 v102, 0.5, v230

.LBB0_717:
	s_andn2_b64 vcc, exec, s[4:5]
	s_cbranch_vccnz .LBB0_799
	v_and_b32_e32 v0, 31, v4
	v_and_or_b32 v2, s7, 32, v0
	v_sub_u32_e64 v3, v2, 8 clamp
	v_min_u32_e32 v3, 48, v3
	v_mul_u32_u24_e32 v4, 0x48, v0
	v_mul_u32_u24_e32 v98, 0x90, v0
	v_or_b32_e32 v0, 32, v97
	v_lshlrev_b32_e32 v1, 3, v5
	v_sub_u32_e32 v0, v0, v3
	v_add_lshl_u32 v99, v1, v4, 1
	v_sub_u32_e32 v1, v97, v3
	v_cmp_gt_u32_e64 s[44:45], 16, v0
	v_or_b32_e32 v0, 1, v97
	v_cmp_gt_u32_e64 s[42:43], 16, v1
	v_or_b32_e32 v1, 33, v97
	v_sub_u32_e32 v0, v0, v3
	v_cmp_gt_u32_e64 s[46:47], 16, v0
	v_sub_u32_e32 v0, v1, v3
	v_cmp_gt_u32_e64 s[48:49], 16, v0
	v_or_b32_e32 v0, 2, v97
	v_or_b32_e32 v1, 34, v97
	v_sub_u32_e32 v0, v0, v3
	v_cmp_gt_u32_e64 s[50:51], 16, v0
	v_sub_u32_e32 v0, v1, v3
	v_cmp_gt_u32_e64 s[52:53], 16, v0
	v_or_b32_e32 v0, 3, v97
	v_or_b32_e32 v1, 35, v97
	v_sub_u32_e32 v0, v0, v3
	v_cmp_gt_u32_e64 s[54:55], 16, v0
	v_sub_u32_e32 v0, v1, v3
	s_mov_b64 s[24:25], s[56:57]
	v_cmp_gt_u32_e64 s[56:57], 16, v0
	v_or_b32_e32 v0, 8, v97
	v_or_b32_e32 v1, 40, v97
	v_sub_u32_e32 v0, v0, v3
	v_cmp_gt_u32_e64 s[58:59], 16, v0
	v_sub_u32_e32 v0, v1, v3
	v_cmp_gt_u32_e64 s[60:61], 16, v0
	v_or_b32_e32 v0, 9, v97
	v_or_b32_e32 v1, 41, v97
	v_sub_u32_e32 v0, v0, v3
	v_cmp_gt_u32_e64 s[62:63], 16, v0
	v_sub_u32_e32 v0, v1, v3
	v_cmp_gt_u32_e64 s[64:65], 16, v0
	v_or_b32_e32 v0, 10, v97
	v_or_b32_e32 v1, 42, v97
	v_sub_u32_e32 v0, v0, v3
	v_cmp_gt_u32_e64 s[66:67], 16, v0
	v_sub_u32_e32 v0, v1, v3
	v_cmp_gt_u32_e64 s[68:69], 16, v0
	v_or_b32_e32 v0, 11, v97
	v_or_b32_e32 v1, 43, v97
	v_sub_u32_e32 v0, v0, v3
	v_cmp_gt_u32_e64 s[70:71], 16, v0
	v_sub_u32_e32 v0, v1, v3
	v_cmp_gt_u32_e64 s[72:73], 16, v0
	v_or_b32_e32 v0, 16, v97
	v_or_b32_e32 v1, 48, v97
	v_sub_u32_e32 v0, v0, v3
	v_cmp_gt_u32_e64 s[74:75], 16, v0
	v_sub_u32_e32 v0, v1, v3
	v_cmp_gt_u32_e64 s[76:77], 16, v0
	v_or_b32_e32 v0, 17, v97
	v_or_b32_e32 v1, 49, v97
	v_sub_u32_e32 v0, v0, v3
	v_cmp_gt_u32_e64 s[78:79], 16, v0
	v_sub_u32_e32 v0, v1, v3
	v_cmp_gt_u32_e64 s[80:81], 16, v0
	v_or_b32_e32 v0, 18, v97
	v_or_b32_e32 v1, 50, v97
	v_sub_u32_e32 v0, v0, v3
	v_cmp_gt_u32_e64 s[82:83], 16, v0
	v_sub_u32_e32 v0, v1, v3
	v_cmp_gt_u32_e64 s[84:85], 16, v0
	v_or_b32_e32 v0, 19, v97
	v_or_b32_e32 v1, 51, v97
	v_sub_u32_e32 v0, v0, v3
	v_cmp_gt_u32_e64 s[86:87], 16, v0
	v_sub_u32_e32 v0, v1, v3
	v_cmp_gt_u32_e64 s[88:89], 16, v0
	v_or_b32_e32 v0, 24, v97
	v_or_b32_e32 v1, 56, v97
	v_sub_u32_e32 v0, v0, v3
	v_cmp_gt_u32_e64 s[90:91], 16, v0
	v_sub_u32_e32 v0, v1, v3
	v_cmp_gt_u32_e64 s[92:93], 16, v0
	v_or_b32_e32 v0, 25, v97
	s_ashr_i32 s19, s6, 7
	v_or_b32_e32 v1, 57, v97
	v_sub_u32_e32 v0, v0, v3
	s_add_i32 s1, s19, s1
	v_cmp_gt_u32_e64 s[94:95], 16, v0
	v_sub_u32_e32 v0, v1, v3
	s_max_i32 s1, s1, 4
	v_cmp_gt_u32_e64 s[96:97], 16, v0
	v_or_b32_e32 v0, 26, v97
	s_add_i32 s1, s1, -4
	v_or_b32_e32 v1, 58, v97
	v_sub_u32_e32 v0, v0, v3
	s_min_u32 s12, s1, 56
	v_cmp_gt_u32_e64 s[4:5], 16, v0
	v_sub_u32_e32 v0, v1, v3
	s_mul_i32 s1, s14, 31
	s_mul_i32 s19, s19, 31
	v_cmp_gt_u32_e64 s[6:7], 16, v0
	v_or_b32_e32 v0, 27, v97
	s_sub_i32 s1, s1, s19
	s_mulk_i32 s0, 0x7c
	v_or_b32_e32 v1, 59, v97
	v_sub_u32_e32 v0, v0, v3
	s_sub_i32 s0, s1, s0
	v_cmp_gt_u32_e64 s[8:9], 16, v0
	v_sub_u32_e32 v0, v1, v3
	s_add_i32 s21, s0, 0x5d
	s_sub_i32 s0, s14, s15
	v_cmp_gt_u32_e64 s[10:11], 16, v0
	v_lshlrev_b32_e32 v0, 2, v2
	s_lshl_b32 s0, s0, 6
	s_add_i32 s13, s12, 8
	s_add_i32 s38, s39, 15
	s_add_i32 s39, s39, 16
	v_sub_u32_e32 v101, 0, v0
	s_add_i32 s1, s0, 0xfffffd40
	v_lshl_add_u32 v0, s14, 6, v92
	s_lshl_b32 s0, s15, 6
	v_subrev_u32_e32 v0, s0, v0
	s_add_u32 s0, s24, s18
	v_add_u32_e32 v0, 0xfffffd40, v0
	s_addc_u32 s15, s25, 0
	v_ashrrev_i32_e32 v1, 31, v0
	s_add_u32 s14, s0, s16
	v_lshlrev_b64 v[0:1], 11, v[0:1]
	s_addc_u32 s15, s15, s17
	v_mov_b32_e32 v14, v131
	v_mov_b32_e32 v15, v131
	v_lshl_add_u64 v[94:95], s[14:15], 0, v[0:1]
	v_mov_b32_e32 v0, v131
	v_mov_b32_e32 v1, v131
	v_mov_b32_e32 v2, v131
	v_mov_b32_e32 v3, v131
	v_mov_b32_e32 v4, v131
	v_mov_b32_e32 v5, v131
	v_mov_b32_e32 v6, v131
	v_mov_b32_e32 v7, v131
	v_mov_b32_e32 v8, v131
	v_mov_b32_e32 v9, v131
	v_mov_b32_e32 v10, v131
	v_mov_b32_e32 v11, v131
	v_mov_b32_e32 v12, v131
	v_mov_b32_e32 v13, v131
	v_lshlrev_b32_e32 v130, 1, v16
	v_mov_b64_e32 v[30:31], v[14:15]
	v_add_u32_e32 v100, 0x1200, v99
	s_mov_b32 s15, 0
	s_mov_b32 s32, 0
	v_mov_b32_e32 v102, 0
	v_mov_b32_e32 v96, 0xff800000
	v_mov_b64_e32 v[28:29], v[12:13]
	v_mov_b64_e32 v[26:27], v[10:11]
	v_mov_b64_e32 v[24:25], v[8:9]
	v_mov_b64_e32 v[22:23], v[6:7]
	v_mov_b64_e32 v[20:21], v[4:5]
	v_mov_b64_e32 v[18:19], v[2:3]
	v_mov_b64_e32 v[16:17], v[0:1]

.LBB0_726:
	s_cmp_lg_u32 s32, 0
	s_cbranch_scc1 .Lna_lean
	s_mul_i32 s24, s15, 0x4800
	s_add_i32 s26, s24, 0
	v_add_u32_e32 v103, s26, v99
	ds_read_b128 v[32:35], v103
	ds_read_b128 v[104:107], v103 offset:32
	v_add_u32_e32 v108, s26, v100
	s_andn2_b64 vcc, exec, s[18:19]
	s_waitcnt lgkmcnt(1)
	v_mfma_f32_32x32x16_bf16 v[48:63], v[32:35], v[64:67], 0
	ds_read_b128 v[32:35], v108
	s_waitcnt lgkmcnt(1)
	v_mfma_f32_32x32x16_bf16 v[48:63], v[104:107], v[68:71], v[48:63]
	ds_read_b128 v[104:107], v108 offset:32
	s_waitcnt lgkmcnt(1)
	v_mfma_f32_32x32x16_bf16 v[32:47], v[32:35], v[64:67], 0
	s_waitcnt lgkmcnt(0)
	v_mfma_f32_32x32x16_bf16 v[32:47], v[104:107], v[68:71], v[32:47]
	ds_read_b128 v[104:107], v103 offset:64
	s_waitcnt lgkmcnt(0)
	v_mfma_f32_32x32x16_bf16 v[48:63], v[104:107], v[72:75], v[48:63]
	ds_read_b128 v[104:107], v108 offset:64
	s_waitcnt lgkmcnt(0)
	v_mfma_f32_32x32x16_bf16 v[32:47], v[104:107], v[72:75], v[32:47]
	ds_read_b128 v[104:107], v103 offset:96
	s_waitcnt lgkmcnt(0)
	v_mfma_f32_32x32x16_bf16 v[48:63], v[104:107], v[76:79], v[48:63]
	ds_read_b128 v[104:107], v108 offset:96
	s_waitcnt lgkmcnt(0)
	v_mfma_f32_32x32x16_bf16 v[32:47], v[104:107], v[76:79], v[32:47]
	s_cbranch_vccnz .LBB0_792
	v_lshl_add_u32 v104, s0, 2, v101
	v_lshl_add_u32 v105, v97, 2, v104
	ds_read_b32 v104, v105 offset:41020
	ds_read_b32 v103, v105 offset:41148
	ds_read_b32 v107, v105 offset:41024
	ds_read_b32 v106, v105 offset:41152
	ds_read_b32 v109, v105 offset:41028
	ds_read_b32 v108, v105 offset:41156
	ds_read_b32 v111, v105 offset:41032
	ds_read_b32 v110, v105 offset:41160
	ds_read_b32 v113, v105 offset:41052
	ds_read_b32 v112, v105 offset:41180
	ds_read_b32 v115, v105 offset:41056
	ds_read_b32 v114, v105 offset:41184
	ds_read_b32 v117, v105 offset:41060
	ds_read_b32 v116, v105 offset:41188
	ds_read_b32 v119, v105 offset:41064
	ds_read_b32 v118, v105 offset:41192
	ds_read_b32 v121, v105 offset:41084
	ds_read_b32 v120, v105 offset:41212
	ds_read_b32 v123, v105 offset:41088
	ds_read_b32 v122, v105 offset:41216
	ds_read_b32 v125, v105 offset:41092
	ds_read_b32 v124, v105 offset:41220
	ds_read_b32 v127, v105 offset:41096
	ds_read_b32 v126, v105 offset:41224
	ds_read_b32 v143, v105 offset:41116
	ds_read_b32 v142, v105 offset:41244
	ds_read_b32 v145, v105 offset:41120
	ds_read_b32 v144, v105 offset:41248
	ds_read_b32 v147, v105 offset:41124
	ds_read_b32 v146, v105 offset:41252
	ds_read_b32 v149, v105 offset:41128
	ds_read_b32 v148, v105 offset:41256
	s_waitcnt lgkmcnt(0)
	v_add_f32_e32 v48, v48, v104
	v_add_f32_e32 v32, v32, v103
	v_add_f32_e32 v49, v49, v107
	v_add_f32_e32 v33, v33, v106
	v_add_f32_e32 v50, v50, v109
	v_add_f32_e32 v34, v34, v108
	v_add_f32_e32 v51, v51, v111
	v_add_f32_e32 v35, v35, v110
	v_add_f32_e32 v52, v52, v113
	v_add_f32_e32 v36, v36, v112
	v_add_f32_e32 v53, v53, v115
	v_add_f32_e32 v37, v37, v114
	v_add_f32_e32 v54, v54, v117
	v_add_f32_e32 v38, v38, v116
	v_add_f32_e32 v55, v55, v119
	v_add_f32_e32 v39, v39, v118
	v_add_f32_e32 v56, v56, v121
	v_add_f32_e32 v40, v40, v120
	v_add_f32_e32 v57, v57, v123
	v_add_f32_e32 v41, v41, v122
	v_add_f32_e32 v58, v58, v125
	v_add_f32_e32 v42, v42, v124
	v_add_f32_e32 v59, v59, v127
	v_add_f32_e32 v43, v43, v126
	v_add_f32_e32 v60, v60, v143
	v_add_f32_e32 v44, v44, v142
	v_add_f32_e32 v61, v61, v145
	v_add_f32_e32 v45, v45, v144
	v_add_f32_e32 v62, v62, v147
	v_add_f32_e32 v46, v46, v146
	v_add_f32_e32 v63, v63, v149
	v_add_f32_e32 v47, v47, v148
	v_cndmask_b32_e64 v48, v169, v48, s[42:43]
	v_cndmask_b32_e64 v32, v169, v32, s[44:45]
	v_cndmask_b32_e64 v49, v169, v49, s[46:47]
	v_cndmask_b32_e64 v33, v169, v33, s[48:49]
	v_cndmask_b32_e64 v50, v169, v50, s[50:51]
	v_cndmask_b32_e64 v34, v169, v34, s[52:53]
	v_cndmask_b32_e64 v51, v169, v51, s[54:55]
	v_cndmask_b32_e64 v35, v169, v35, s[56:57]
	v_cndmask_b32_e64 v52, v169, v52, s[58:59]
	v_cndmask_b32_e64 v36, v169, v36, s[60:61]
	v_cndmask_b32_e64 v53, v169, v53, s[62:63]
	v_cndmask_b32_e64 v37, v169, v37, s[64:65]
	v_cndmask_b32_e64 v54, v169, v54, s[66:67]
	v_cndmask_b32_e64 v38, v169, v38, s[68:69]
	v_cndmask_b32_e64 v55, v169, v55, s[70:71]
	v_cndmask_b32_e64 v39, v169, v39, s[72:73]
	v_cndmask_b32_e64 v56, v169, v56, s[74:75]
	v_cndmask_b32_e64 v40, v169, v40, s[76:77]
	v_cndmask_b32_e64 v57, v169, v57, s[78:79]
	v_cndmask_b32_e64 v41, v169, v41, s[80:81]
	v_cndmask_b32_e64 v58, v169, v58, s[82:83]
	v_cndmask_b32_e64 v42, v169, v42, s[84:85]
	v_cndmask_b32_e64 v59, v169, v59, s[86:87]
	v_cndmask_b32_e64 v43, v169, v43, s[88:89]
	v_cndmask_b32_e64 v60, v169, v60, s[90:91]
	v_cndmask_b32_e64 v44, v169, v44, s[92:93]
	v_cndmask_b32_e64 v61, v169, v61, s[94:95]
	v_cndmask_b32_e64 v45, v169, v45, s[96:97]
	v_cndmask_b32_e64 v62, v169, v62, s[4:5]
	v_cndmask_b32_e64 v46, v169, v46, s[6:7]
	v_cndmask_b32_e64 v63, v169, v63, s[8:9]
	v_cndmask_b32_e64 v47, v169, v47, s[10:11]

.LBB0_794:
	v_pk_add_f32 v[48:49], v[48:49], v[96:97] op_sel_hi:[1,0] neg_lo:[0,1] neg_hi:[0,1]
	v_pk_add_f32 v[32:33], v[32:33], v[96:97] op_sel_hi:[1,0] neg_lo:[0,1] neg_hi:[0,1]
	v_exp_f32_e32 v104, v48
	v_exp_f32_e32 v105, v49
	v_exp_f32_e32 v32, v32
	v_exp_f32_e32 v33, v33
	v_pk_add_f32 v[50:51], v[50:51], v[96:97] op_sel_hi:[1,0] neg_lo:[0,1] neg_hi:[0,1]
	v_pk_add_f32 v[34:35], v[34:35], v[96:97] op_sel_hi:[1,0] neg_lo:[0,1] neg_hi:[0,1]
	v_exp_f32_e32 v106, v50
	v_exp_f32_e32 v107, v51
	v_exp_f32_e32 v34, v34
	v_exp_f32_e32 v35, v35
	v_pk_add_f32 v[50:51], v[52:53], v[96:97] op_sel_hi:[1,0] neg_lo:[0,1] neg_hi:[0,1]
	v_pk_add_f32 v[48:49], v[104:105], 0 op_sel_hi:[1,0]
	v_pk_add_f32 v[36:37], v[36:37], v[96:97] op_sel_hi:[1,0] neg_lo:[0,1] neg_hi:[0,1]
	v_exp_f32_e32 v108, v50
	v_exp_f32_e32 v109, v51
	v_pk_add_f32 v[48:49], v[32:33], v[48:49]
	v_exp_f32_e32 v36, v36
	v_exp_f32_e32 v37, v37
	v_pk_add_f32 v[48:49], v[106:107], v[48:49]
	v_add3_u32 v103, s26, v98, v90
	v_pk_add_f32 v[48:49], v[34:35], v[48:49]
	v_pk_add_f32 v[58:59], v[58:59], v[96:97] op_sel_hi:[1,0] neg_lo:[0,1] neg_hi:[0,1]
	v_pk_add_f32 v[48:49], v[108:109], v[48:49]
	v_pk_add_f32 v[38:39], v[38:39], v[96:97] op_sel_hi:[1,0] neg_lo:[0,1] neg_hi:[0,1]
	v_pk_add_f32 v[52:53], v[36:37], v[48:49]
	v_pk_add_f32 v[48:49], v[54:55], v[96:97] op_sel_hi:[1,0] neg_lo:[0,1] neg_hi:[0,1]
	v_pk_add_f32 v[54:55], v[56:57], v[96:97] op_sel_hi:[1,0] neg_lo:[0,1] neg_hi:[0,1]
	v_exp_f32_e32 v110, v48
	v_exp_f32_e32 v111, v49
	ds_read_b128 v[48:51], v103 offset:9216
	v_exp_f32_e32 v112, v54
	v_exp_f32_e32 v113, v55
	v_cvt_pk_bf16_f32 v54, v104, v105
	v_cvt_pk_bf16_f32 v55, v106, v107
	ds_read_b128 v[104:107], v103 offset:13824
	v_cvt_pk_bf16_f32 v56, v108, v109
	v_cvt_pk_bf16_f32 v57, v110, v111
	v_pk_add_f32 v[62:63], v[62:63], v[96:97] op_sel_hi:[1,0] neg_lo:[0,1] neg_hi:[0,1]
	v_exp_f32_e32 v38, v38
	s_waitcnt lgkmcnt(1)
	v_mfma_f32_32x32x16_bf16 v[0:15], v[48:51], v[54:57], v[0:15]
	v_exp_f32_e32 v48, v58
	v_exp_f32_e32 v49, v59
	v_pk_add_f32 v[50:51], v[60:61], v[96:97] op_sel_hi:[1,0] neg_lo:[0,1] neg_hi:[0,1]
	ds_read_b128 v[58:61], v103 offset:9248
	v_exp_f32_e32 v39, v39
	v_exp_f32_e32 v50, v50
	v_exp_f32_e32 v51, v51
	s_waitcnt lgkmcnt(1)
	v_mfma_f32_32x32x16_bf16 v[16:31], v[104:107], v[54:57], v[16:31]
	ds_read_b128 v[104:107], v103 offset:13856
	v_exp_f32_e32 v62, v62
	v_exp_f32_e32 v63, v63
	v_pk_add_f32 v[52:53], v[110:111], v[52:53]
	v_cvt_pk_bf16_f32 v54, v112, v113
	v_cvt_pk_bf16_f32 v55, v48, v49
	v_cvt_pk_bf16_f32 v56, v50, v51
	v_cvt_pk_bf16_f32 v57, v62, v63
	v_pk_add_f32 v[52:53], v[38:39], v[52:53]
	v_cvt_pk_bf16_f32 v32, v32, v33
	v_cvt_pk_bf16_f32 v33, v34, v35
	v_cvt_pk_bf16_f32 v34, v36, v37
	v_cvt_pk_bf16_f32 v35, v38, v39
	ds_read_b128 v[36:39], v103 offset:13888
	s_waitcnt lgkmcnt(2)
	v_mfma_f32_32x32x16_bf16 v[0:15], v[58:61], v[54:57], v[0:15]
	ds_read_b128 v[58:61], v103 offset:9280
	v_add_f32_e64 v40, v40, -v96
	v_add_f32_e64 v41, v41, -v96
	v_add_f32_e64 v46, v46, -v96
	v_add_f32_e64 v47, v47, -v96
	v_exp_f32_e32 v108, v40
	v_exp_f32_e32 v109, v41
	v_pk_add_f32 v[40:41], v[112:113], v[52:53]
	v_exp_f32_e32 v46, v46
	s_waitcnt lgkmcnt(2)
	v_mfma_f32_32x32x16_bf16 v[16:31], v[104:107], v[54:57], v[16:31]
	v_add_f32_e64 v52, v108, v40
	v_add_f32_e64 v53, v109, v41
	v_add_f32_e64 v40, v42, -v96
	v_add_f32_e64 v41, v43, -v96
	v_exp_f32_e32 v47, v47
	v_exp_f32_e32 v54, v40
	v_exp_f32_e32 v55, v41
	v_pk_add_f32 v[40:41], v[44:45], v[96:97] op_sel_hi:[1,0] neg_lo:[0,1] neg_hi:[0,1]
	s_nop 0
	v_exp_f32_e32 v44, v40
	v_exp_f32_e32 v45, v41
	ds_read_b128 v[40:43], v103 offset:9312
	s_waitcnt lgkmcnt(2)
	v_mfma_f32_32x32x16_bf16 v[16:31], v[36:39], v[32:35], v[16:31]
	ds_read_b128 v[36:39], v103 offset:13920
	s_waitcnt lgkmcnt(2)
	v_mfma_f32_32x32x16_bf16 v[0:15], v[58:61], v[32:35], v[0:15]
	v_cvt_pk_bf16_f32 v32, v108, v109
	v_cvt_pk_bf16_f32 v33, v54, v55
	v_cvt_pk_bf16_f32 v34, v44, v45
	v_cvt_pk_bf16_f32 v35, v46, v47
	s_waitcnt lgkmcnt(1)
	s_nop 0
	v_mfma_f32_32x32x16_bf16 v[0:15], v[40:43], v[32:35], v[0:15]
	v_add_f32_e64 v40, v48, v52
	v_add_f32_e64 v41, v49, v53
	v_add_f32_e64 v40, v54, v40
	v_add_f32_e64 v41, v55, v41
	v_add_f32_e64 v40, v50, v40
	v_add_f32_e64 v41, v51, v41
	v_pk_add_f32 v[40:41], v[44:45], v[40:41]
	s_waitcnt lgkmcnt(0)
	v_mfma_f32_32x32x16_bf16 v[16:31], v[36:39], v[32:35], v[16:31]
	v_add_f32_e64 v40, v62, v40
	v_add_f32_e64 v41, v63, v41
	v_add_f32_e64 v40, v46, v40
	v_add_f32_e64 v41, v47, v41
	v_add_f32_e32 v40, v40, v41
	v_add_f32_e32 v102, v102, v40
	s_mov_b32 s32, 1
	v_sub_f32_e32 v214, 0, v96
	v_sub_f32_e32 v215, 0, v96
	v_sub_f32_e32 v216, 0, v96
	v_sub_f32_e32 v217, 0, v96
	v_sub_f32_e32 v218, 0, v96
	v_sub_f32_e32 v219, 0, v96
	v_sub_f32_e32 v220, 0, v96
	v_sub_f32_e32 v221, 0, v96
	v_sub_f32_e32 v222, 0, v96
	v_sub_f32_e32 v223, 0, v96
	v_sub_f32_e32 v224, 0, v96
	v_sub_f32_e32 v225, 0, v96
	v_sub_f32_e32 v226, 0, v96
	v_sub_f32_e32 v227, 0, v96
	v_sub_f32_e32 v228, 0, v96
	v_sub_f32_e32 v229, 0, v96
	v_mov_b32_e32 v230, 0
	v_mov_b32_e32 v231, 0
	v_mov_b32_e32 v232, 0
	v_mov_b32_e32 v233, 0
	v_mov_b32_e32 v234, 0
	v_mov_b32_e32 v235, 0
	v_mov_b32_e32 v236, 0
	v_mov_b32_e32 v237, 0
	v_mov_b32_e32 v238, 0
	v_mov_b32_e32 v239, 0
	v_mov_b32_e32 v240, 0
	v_mov_b32_e32 v241, 0
	v_mov_b32_e32 v242, 0
	v_mov_b32_e32 v243, 0
	v_mov_b32_e32 v244, 0
	v_mov_b32_e32 v245, 0
	v_mov_b32_e32 v246, 0x3f803f80
	v_mov_b32_e32 v247, 0x3f803f80
	v_mov_b32_e32 v248, 0x3f803f80
	v_mov_b32_e32 v249, 0x3f803f80
	s_branch .LBB0_795
.Lna_rare:
	v_frexp_exp_i32_f32_e32 v32, v230
	v_sub_u32_e32 v33, 0, v32
	v_cvt_f32_i32_e32 v35, v32
	v_ldexp_f32 v34, 1.0, v33
	v_pk_mul_f32 v[0:1], v[0:1], v[34:35] op_sel_hi:[1,0]
	v_pk_mul_f32 v[2:3], v[2:3], v[34:35] op_sel_hi:[1,0]
	v_pk_mul_f32 v[4:5], v[4:5], v[34:35] op_sel_hi:[1,0]
	v_pk_mul_f32 v[6:7], v[6:7], v[34:35] op_sel_hi:[1,0]
	v_pk_mul_f32 v[8:9], v[8:9], v[34:35] op_sel_hi:[1,0]
	v_pk_mul_f32 v[10:11], v[10:11], v[34:35] op_sel_hi:[1,0]
	v_pk_mul_f32 v[12:13], v[12:13], v[34:35] op_sel_hi:[1,0]
	v_pk_mul_f32 v[14:15], v[14:15], v[34:35] op_sel_hi:[1,0]
	v_pk_mul_f32 v[16:17], v[16:17], v[34:35] op_sel_hi:[1,0]
	v_pk_mul_f32 v[18:19], v[18:19], v[34:35] op_sel_hi:[1,0]
	v_pk_mul_f32 v[20:21], v[20:21], v[34:35] op_sel_hi:[1,0]
	v_pk_mul_f32 v[22:23], v[22:23], v[34:35] op_sel_hi:[1,0]
	v_pk_mul_f32 v[24:25], v[24:25], v[34:35] op_sel_hi:[1,0]
	v_pk_mul_f32 v[26:27], v[26:27], v[34:35] op_sel_hi:[1,0]
	v_pk_mul_f32 v[28:29], v[28:29], v[34:35] op_sel_hi:[1,0]
	v_pk_mul_f32 v[30:31], v[30:31], v[34:35] op_sel_hi:[1,0]
	v_pk_mul_f32 v[230:231], v[230:231], v[34:35] op_sel_hi:[1,0]
	v_pk_mul_f32 v[232:233], v[232:233], v[34:35] op_sel_hi:[1,0]
	v_pk_mul_f32 v[234:235], v[234:235], v[34:35] op_sel_hi:[1,0]
	v_pk_mul_f32 v[236:237], v[236:237], v[34:35] op_sel_hi:[1,0]
	v_pk_mul_f32 v[238:239], v[238:239], v[34:35] op_sel_hi:[1,0]
	v_pk_mul_f32 v[240:241], v[240:241], v[34:35] op_sel_hi:[1,0]
	v_pk_mul_f32 v[242:243], v[242:243], v[34:35] op_sel_hi:[1,0]
	v_pk_mul_f32 v[244:245], v[244:245], v[34:35] op_sel_hi:[1,0]
	v_mul_f32_e32 v102, v102, v34
	v_sub_f32_e32 v214, v214, v35
	v_sub_f32_e32 v215, v215, v35
	v_sub_f32_e32 v216, v216, v35
	v_sub_f32_e32 v217, v217, v35
	v_sub_f32_e32 v218, v218, v35
	v_sub_f32_e32 v219, v219, v35
	v_sub_f32_e32 v220, v220, v35
	v_sub_f32_e32 v221, v221, v35
	v_sub_f32_e32 v222, v222, v35
	v_sub_f32_e32 v223, v223, v35
	v_sub_f32_e32 v224, v224, v35
	v_sub_f32_e32 v225, v225, v35
	v_sub_f32_e32 v226, v226, v35
	v_sub_f32_e32 v227, v227, v35
	v_sub_f32_e32 v228, v228, v35
	v_sub_f32_e32 v229, v229, v35
	s_branch .Lna_rb
.Lna_ctx:
	ds_read_b128 v[104:107], v103
	ds_read_b128 v[108:111], v103 offset:32
	ds_read_b128 v[112:115], v103 offset:64
	ds_read_b128 v[116:119], v103 offset:96
	ds_read_b128 v[120:123], v103 offset:4608
	ds_read_b128 v[124:127], v103 offset:4640
	ds_read_b128 v[142:145], v103 offset:4672
	ds_read_b128 v[146:149], v103 offset:4704
	s_waitcnt lgkmcnt(7)
	v_mfma_f32_32x32x16_bf16 v[48:63], v[104:107], v[64:67], v[214:229]
	s_waitcnt lgkmcnt(6)
	v_mfma_f32_32x32x16_bf16 v[48:63], v[108:111], v[68:71], v[48:63]
	s_waitcnt lgkmcnt(5)
	v_mfma_f32_32x32x16_bf16 v[48:63], v[112:115], v[72:75], v[48:63]
	s_waitcnt lgkmcnt(4)
	v_mfma_f32_32x32x16_bf16 v[48:63], v[116:119], v[76:79], v[48:63]
	s_waitcnt lgkmcnt(3)
	v_mfma_f32_32x32x16_bf16 v[32:47], v[120:123], v[64:67], v[214:229]
	s_waitcnt lgkmcnt(2)
	v_mfma_f32_32x32x16_bf16 v[32:47], v[124:127], v[68:71], v[32:47]
	s_waitcnt lgkmcnt(1)
	v_mfma_f32_32x32x16_bf16 v[32:47], v[142:145], v[72:75], v[32:47]
	s_waitcnt lgkmcnt(0)
	v_mfma_f32_32x32x16_bf16 v[32:47], v[146:149], v[76:79], v[32:47]
	s_branch .Lna_pv
.Lna_lean:
	s_mul_i32 s24, s15, 0x4800
	s_add_i32 s26, s24, 0
	v_add_u32_e32 v103, s26, v99
	v_cmp_lt_f32_e32 vcc, 0x53800000, v230
	s_cbranch_vccnz .Lna_rare
.Lna_rb:
	s_cmp_lg_u64 s[18:19], 0
	s_cbranch_scc0 .Lna_ctx
	v_lshl_add_u32 v96, s0, 2, v101
	v_lshl_add_u32 v96, v97, 2, v96
	v_add_u32_e32 v96, 0xa03c, v96
	ds_read2_b32 v[182:183], v96 offset0:0 offset1:1
	ds_read2_b32 v[184:185], v96 offset0:2 offset1:3
	ds_read2_b32 v[186:187], v96 offset0:8 offset1:9
	ds_read2_b32 v[188:189], v96 offset0:10 offset1:11
	ds_read2_b32 v[190:191], v96 offset0:16 offset1:17
	ds_read2_b32 v[192:193], v96 offset0:18 offset1:19
	ds_read2_b32 v[194:195], v96 offset0:24 offset1:25
	ds_read2_b32 v[196:197], v96 offset0:26 offset1:27
	ds_read_b128 v[104:107], v103
	ds_read_b128 v[108:111], v103 offset:32
	ds_read_b128 v[112:115], v103 offset:64
	ds_read_b128 v[116:119], v103 offset:96
	s_waitcnt lgkmcnt(4)
	v_pk_add_f32 v[182:183], v[182:183], v[214:215]
	v_pk_add_f32 v[184:185], v[184:185], v[214:215]
	v_pk_add_f32 v[186:187], v[186:187], v[214:215]
	v_pk_add_f32 v[188:189], v[188:189], v[214:215]
	v_pk_add_f32 v[190:191], v[190:191], v[214:215]
	v_pk_add_f32 v[192:193], v[192:193], v[214:215]
	v_pk_add_f32 v[194:195], v[194:195], v[214:215]
	v_pk_add_f32 v[196:197], v[196:197], v[214:215]
	v_cndmask_b32_e64 v182, v169, v182, s[42:43]
	v_cndmask_b32_e64 v183, v169, v183, s[46:47]
	v_cndmask_b32_e64 v184, v169, v184, s[50:51]
	v_cndmask_b32_e64 v185, v169, v185, s[54:55]
	v_cndmask_b32_e64 v186, v169, v186, s[58:59]
	v_cndmask_b32_e64 v187, v169, v187, s[62:63]
	v_cndmask_b32_e64 v188, v169, v188, s[66:67]
	v_cndmask_b32_e64 v189, v169, v189, s[70:71]
	v_cndmask_b32_e64 v190, v169, v190, s[74:75]
	v_cndmask_b32_e64 v191, v169, v191, s[78:79]
	v_cndmask_b32_e64 v192, v169, v192, s[82:83]
	v_cndmask_b32_e64 v193, v169, v193, s[86:87]
	v_cndmask_b32_e64 v194, v169, v194, s[90:91]
	v_cndmask_b32_e64 v195, v169, v195, s[94:95]
	v_cndmask_b32_e64 v196, v169, v196, s[4:5]
	v_cndmask_b32_e64 v197, v169, v197, s[8:9]
	ds_read2_b32 v[198:199], v96 offset0:32 offset1:33
	ds_read2_b32 v[200:201], v96 offset0:34 offset1:35
	ds_read2_b32 v[202:203], v96 offset0:40 offset1:41
	ds_read2_b32 v[204:205], v96 offset0:42 offset1:43
	ds_read2_b32 v[206:207], v96 offset0:48 offset1:49
	ds_read2_b32 v[208:209], v96 offset0:50 offset1:51
	ds_read2_b32 v[210:211], v96 offset0:56 offset1:57
	ds_read2_b32 v[212:213], v96 offset0:58 offset1:59
	s_waitcnt lgkmcnt(8)
	v_mfma_f32_32x32x16_bf16 v[48:63], v[104:107], v[64:67], v[182:197]
	ds_read_b128 v[120:123], v103 offset:4608
	ds_read_b128 v[124:127], v103 offset:4640
	ds_read_b128 v[142:145], v103 offset:4672
	ds_read_b128 v[146:149], v103 offset:4704
	v_mfma_f32_32x32x16_bf16 v[48:63], v[108:111], v[68:71], v[48:63]
	v_mfma_f32_32x32x16_bf16 v[48:63], v[112:115], v[72:75], v[48:63]
	v_mfma_f32_32x32x16_bf16 v[48:63], v[116:119], v[76:79], v[48:63]
	s_waitcnt lgkmcnt(4)
	v_pk_add_f32 v[198:199], v[198:199], v[214:215]
	v_pk_add_f32 v[200:201], v[200:201], v[214:215]
	v_pk_add_f32 v[202:203], v[202:203], v[214:215]
	v_pk_add_f32 v[204:205], v[204:205], v[214:215]
	v_pk_add_f32 v[206:207], v[206:207], v[214:215]
	v_pk_add_f32 v[208:209], v[208:209], v[214:215]
	v_pk_add_f32 v[210:211], v[210:211], v[214:215]
	v_pk_add_f32 v[212:213], v[212:213], v[214:215]
	v_cndmask_b32_e64 v198, v169, v198, s[44:45]
	v_cndmask_b32_e64 v199, v169, v199, s[48:49]
	v_cndmask_b32_e64 v200, v169, v200, s[52:53]
	v_cndmask_b32_e64 v201, v169, v201, s[56:57]
	v_cndmask_b32_e64 v202, v169, v202, s[60:61]
	v_cndmask_b32_e64 v203, v169, v203, s[64:65]
	v_cndmask_b32_e64 v204, v169, v204, s[68:69]
	v_cndmask_b32_e64 v205, v169, v205, s[72:73]
	v_cndmask_b32_e64 v206, v169, v206, s[76:77]
	v_cndmask_b32_e64 v207, v169, v207, s[80:81]
	v_cndmask_b32_e64 v208, v169, v208, s[84:85]
	v_cndmask_b32_e64 v209, v169, v209, s[88:89]
	v_cndmask_b32_e64 v210, v169, v210, s[92:93]
	v_cndmask_b32_e64 v211, v169, v211, s[96:97]
	v_cndmask_b32_e64 v212, v169, v212, s[6:7]
	v_cndmask_b32_e64 v213, v169, v213, s[10:11]
	s_waitcnt lgkmcnt(0)
	s_nop 1
	v_mfma_f32_32x32x16_bf16 v[32:47], v[120:123], v[64:67], v[198:213]
	v_mfma_f32_32x32x16_bf16 v[32:47], v[124:127], v[68:71], v[32:47]
	v_mfma_f32_32x32x16_bf16 v[32:47], v[142:145], v[72:75], v[32:47]
	v_mfma_f32_32x32x16_bf16 v[32:47], v[146:149], v[76:79], v[32:47]
.Lna_pv:
	v_add3_u32 v103, s26, v98, v90
	ds_read_b128 v[104:107], v103 offset:9216
	ds_read_b128 v[108:111], v103 offset:13824
	ds_read_b128 v[112:115], v103 offset:9248
	ds_read_b128 v[116:119], v103 offset:13856
	ds_read_b128 v[120:123], v103 offset:9280
	ds_read_b128 v[124:127], v103 offset:13888
	ds_read_b128 v[142:145], v103 offset:9312
	ds_read_b128 v[146:149], v103 offset:13920
	v_exp_f32_e32 v48, v48
	v_exp_f32_e32 v49, v49
	v_exp_f32_e32 v50, v50
	v_exp_f32_e32 v51, v51
	v_exp_f32_e32 v52, v52
	v_exp_f32_e32 v53, v53
	v_exp_f32_e32 v54, v54
	v_exp_f32_e32 v55, v55
	v_cvt_pk_bf16_f32 v48, v48, v49
	v_cvt_pk_bf16_f32 v49, v50, v51
	v_cvt_pk_bf16_f32 v50, v52, v53
	v_cvt_pk_bf16_f32 v51, v54, v55
	v_exp_f32_e32 v56, v56
	v_exp_f32_e32 v57, v57
	v_exp_f32_e32 v58, v58
	v_exp_f32_e32 v59, v59
	v_exp_f32_e32 v60, v60
	v_exp_f32_e32 v61, v61
	v_exp_f32_e32 v62, v62
	v_exp_f32_e32 v63, v63
	s_waitcnt lgkmcnt(6)
	v_mfma_f32_32x32x16_bf16 v[0:15], v[104:107], v[48:51], v[0:15]
	v_mfma_f32_32x32x16_bf16 v[16:31], v[108:111], v[48:51], v[16:31]
	v_mfma_f32_32x32x16_bf16 v[230:245], v[246:249], v[48:51], v[230:245]
	v_cvt_pk_bf16_f32 v56, v56, v57
	v_cvt_pk_bf16_f32 v57, v58, v59
	v_cvt_pk_bf16_f32 v58, v60, v61
	v_cvt_pk_bf16_f32 v59, v62, v63
	v_exp_f32_e32 v32, v32
	v_exp_f32_e32 v33, v33
	v_exp_f32_e32 v34, v34
	v_exp_f32_e32 v35, v35
	v_exp_f32_e32 v36, v36
	v_exp_f32_e32 v37, v37
	v_exp_f32_e32 v38, v38
	v_exp_f32_e32 v39, v39
	s_waitcnt lgkmcnt(4)
	v_mfma_f32_32x32x16_bf16 v[0:15], v[112:115], v[56:59], v[0:15]
	v_mfma_f32_32x32x16_bf16 v[16:31], v[116:119], v[56:59], v[16:31]
	v_mfma_f32_32x32x16_bf16 v[230:245], v[246:249], v[56:59], v[230:245]
	v_cvt_pk_bf16_f32 v32, v32, v33
	v_cvt_pk_bf16_f32 v33, v34, v35
	v_cvt_pk_bf16_f32 v34, v36, v37
	v_cvt_pk_bf16_f32 v35, v38, v39
	v_exp_f32_e32 v40, v40
	v_exp_f32_e32 v41, v41
	v_exp_f32_e32 v42, v42
	v_exp_f32_e32 v43, v43
	v_exp_f32_e32 v44, v44
	v_exp_f32_e32 v45, v45
	v_exp_f32_e32 v46, v46
	v_exp_f32_e32 v47, v47
	s_waitcnt lgkmcnt(2)
	v_mfma_f32_32x32x16_bf16 v[0:15], v[120:123], v[32:35], v[0:15]
	v_mfma_f32_32x32x16_bf16 v[16:31], v[124:127], v[32:35], v[16:31]
	v_mfma_f32_32x32x16_bf16 v[230:245], v[246:249], v[32:35], v[230:245]
	v_cvt_pk_bf16_f32 v40, v40, v41
	v_cvt_pk_bf16_f32 v41, v42, v43
	v_cvt_pk_bf16_f32 v42, v44, v45
	v_cvt_pk_bf16_f32 v43, v46, v47
	s_nop 1
	s_waitcnt lgkmcnt(0)
	v_mfma_f32_32x32x16_bf16 v[0:15], v[142:145], v[40:43], v[0:15]
	v_mfma_f32_32x32x16_bf16 v[16:31], v[146:149], v[40:43], v[16:31]
	v_mfma_f32_32x32x16_bf16 v[230:245], v[246:249], v[40:43], v[230:245]
